# up GEMM produces gate and val tile columns interleaved (g0 v0 g1 v1 ...)
# baseline (speedup 1.0000x reference)
; __device__ __forceinline__ int fresh_lane() { int l; asm volatile("v_mbcnt_lo_u32_b32 %0, -1, 0\n\tv_mbcnt_hi_u32_b32 %0, -1, %0" : "=v"(l)); return l; }
; #define PG8_STAGE(bufoff, gbase, voff) do { _Pragma("unroll") for (int _i = 0; _i < 2; ++_i) \
;         __builtin_amdgcn_global_load_lds((const unsigned*)((const char*)(gbase) + (voff)[_i]), (LAS unsigned*)(lds + (bufoff) + ldsw + _i * 8192), 16, 0, 0); } while (0)
; #define PG8_WAIT_V(n) asm volatile("s_waitcnt vmcnt(" #n ")" ::: "memory")
; #define PG8_BAR __builtin_amdgcn_s_barrier()
; template <class Epi, class Sched, bool ALIGN_EPI>
; __device__ __forceinline__ void gemm_phase(LAS unsigned char* lds, const int wid, const int lda_, const int ldb_, const int K_, const Sched& S, const Epi& E) {
;     ...
;     const int lane = fresh_lane(), tid = wid * 64 + lane;
;     const int wr = wid >> 2, wc = wid & 3, fr = lane & 15, fq = lane >> 4;
;     unsigned voffA[2], voffB[2];
; #pragma unroll
;     for (int i = 0; i < 2; ++i) { int R, C; stage_rc(tid * 16 + i * 8192, R, C); const int Rb = Epi::PERM ? ((R & ~31) + perm32(R & 31)) : R;
;         voffA[i] = (unsigned)(R * lda + C) * 2u; voffB[i] = (unsigned)(Rb * ldb + C) * 2u; }
;     const size_t kstep = (size_t)(BK * 2);
;     const size_t hstepA = (size_t)HALF * lda * 2, hstepB = (size_t)HALF * ldb * 2;
;     const unsigned ldsw = (unsigned)wid * 1024u;
;     const int aoff = lds_byte(wr * 64 + fr, fq * 8), boff = lds_byte(wc * 32 + fr, fq * 8);
;     ...
;     Unit cur, nxt; int ui = 0;
;     if (!S.next(0, cur)) return;
;     f32x4 acc[2][2][4][2];
; #pragma unroll
;     for (int a = 0; a < 2; ++a)
; #pragma unroll
;         for (int b = 0; b < 2; ++b)
; #pragma unroll
;             for (int m = 0; m < 4; ++m)
; #pragma unroll
;                 for (int n = 0; n < 2; ++n) acc[a][b][m][n] = (f32x4){0.f, 0.f, 0.f, 0.f};
;     bf16x8 At[4][2], B0[2][2], B1[2][2];
;     const char* cA = S.a(cur); const char* cB = S.b(cur);
;     PG8_STAGE(PG8_SB(0, 0), cB, voffB); PG8_STAGE(PG8_SB(0, 1), cB + hstepB, voffB); PG8_STAGE(PG8_SA(0, 0), cA, voffA); PG8_STAGE(PG8_SA(0, 1), cA + hstepA, voffA);
;     if (wr == 1) PG8_BAR;
;     PG8_WAIT_V(2); PG8_BAR;
;     PG8_STAGE(PG8_SB(1, 0), cB + kstep, voffB); PG8_STAGE(PG8_SA(1, 0), cA + kstep, voffA); PG8_STAGE(PG8_SB(1, 1), cB + hstepB + kstep, voffB);
.LBB0_1112:
	s_andn2_b64 vcc, exec, s[0:1]
	s_cbranch_vccnz .LBB0_1200
	v_readlane_b32 s0, v255, 35
	s_lshr_b32 s6, s0, 8
	s_mul_i32 s0, s6, 44
	s_cmp_ge_i32 s2, s0
	s_movk_i32 s34, 0x800
	s_movk_i32 s4, 0x800
	s_waitcnt vmcnt(0)
	v_mbcnt_lo_u32_b32 v0, -1, 0
	v_mbcnt_hi_u32_b32 v0, -1, v0
	v_mbcnt_lo_u32_b32 v6, -1, 0
	v_mbcnt_hi_u32_b32 v6, -1, v6
	s_cbranch_scc1 .LBB0_1125
	v_lshl_add_u32 v3, v6, 4, s3
	v_add_u32_e32 v0, 0x2000, v3
	v_ashrrev_i32_e32 v1, 31, v0
	v_lshrrev_b32_e32 v1, 22, v1
	v_add_u32_e32 v1, v0, v1
	v_ashrrev_i32_e32 v1, 10, v1
	v_mul_i32_i24_e32 v2, 0x400, v1
	v_sub_u32_e32 v0, v0, v2
	v_lshrrev_b32_e32 v2, 4, v0
	s_lshr_b32 s7, s0, 3
	v_bitop3_b32 v2, v2, v0, 32 bitop3:0x6c
	s_mul_i32 s5, s82, 0x2c00000
	s_or_b32 s14, s7, 1
	v_ashrrev_i32_e32 v0, 31, v2
	s_add_u32 s5, s66, s5
	v_lshrrev_b32_e32 v0, 26, v0
	s_addc_u32 s10, s67, 0
	v_add_u32_e32 v4, v2, v0
	v_lshlrev_b32_e32 v5, 3, v1
	s_add_u32 s15, s5, 0x9600000
	v_ashrrev_i32_e32 v0, 6, v4
	v_and_b32_e32 v5, -16, v5
	s_addc_u32 s26, s10, 0
	s_ashr_i32 s5, s4, 31
	v_add_u32_e32 v5, v0, v5
	s_lshl_b64 s[30:31], s[4:5], 8
	v_and_b32_e32 v0, 3, v0
	s_mov_b32 s5, 0x7fffffe0
	v_lshrrev_b32_e32 v7, 2, v5
	v_lshlrev_b32_e32 v8, 1, v5
	v_and_or_b32 v0, v5, s5, v0
	v_and_b32_e32 v7, 4, v7
	v_and_b32_e32 v8, 24, v8
	v_or3_b32 v0, v0, v7, v8
	v_mul_lo_u32 v7, v0, s4
	v_lshlrev_b32_e32 v0, 5, v1
	v_and_b32_e32 v1, 0xffc0, v4
	v_sub_u32_e32 v1, v2, v1
	v_lshrrev_b16_e32 v2, 7, v1
	v_and_b32_e32 v2, 1, v2
	v_add_u16_e32 v1, v1, v2
	v_ashrrev_i16_sdwa v1, v239, sext(v1) dst_sel:DWORD dst_unused:UNUSED_PAD src0_sel:DWORD src1_sel:BYTE_0
	v_and_b32_e32 v0, 32, v0
	v_bfe_i32 v1, v1, 0, 16
	v_add_u32_e32 v4, v0, v1
	v_mul_lo_u32 v2, v5, s34
	v_add_lshl_u32 v128, v7, v4, 1
	v_add_lshl_u32 v130, v4, v2, 1
	v_ashrrev_i32_e32 v4, 31, v3
	v_lshrrev_b32_e32 v4, 22, v4
	v_add_u32_e32 v4, v3, v4
	v_ashrrev_i32_e32 v4, 10, v4
	v_mul_i32_i24_e32 v5, 0x400, v4
	v_sub_u32_e32 v3, v3, v5
	v_lshrrev_b32_e32 v5, 4, v3
	v_bitop3_b32 v5, v5, v3, 32 bitop3:0x6c
	v_ashrrev_i32_e32 v3, 31, v5
	v_lshrrev_b32_e32 v3, 26, v3
	v_add_u32_e32 v7, v5, v3
	v_lshlrev_b32_e32 v8, 3, v4
	v_ashrrev_i32_e32 v3, 6, v7
	v_and_b32_e32 v8, -16, v8
	v_add_u32_e32 v8, v3, v8
	v_and_b32_e32 v3, 3, v3
	v_lshrrev_b32_e32 v9, 2, v8
	v_lshlrev_b32_e32 v10, 1, v8
	v_and_or_b32 v3, v8, s5, v3
	v_and_b32_e32 v9, 4, v9
	v_and_b32_e32 v10, 24, v10
	v_or3_b32 v3, v3, v9, v10
	s_ashr_i32 s35, s34, 31
	v_mul_lo_u32 v9, v3, s4
	v_readlane_b32 s4, v252, 55
	s_lshl_b64 s[10:11], s[34:35], 8
	v_readlane_b32 s5, v252, 56
	s_and_b64 s[4:5], s[4:5], exec
	s_cselect_b32 s4, s14, s7
	v_readlane_b32 s5, v253, 0
	s_mul_i32 s4, s4, s5
	v_readlane_b32 s5, v253, 56
	s_add_i32 s4, s4, s5
	s_mul_hi_i32 s5, s4, 0x2e8ba2e9
	s_lshr_b32 s17, s5, 31
	s_ashr_i32 s5, s5, 6
	s_add_i32 s5, s5, s17
	s_lshl_b32 s17, s5, 3
	s_sub_i32 s27, s6, s17
	s_min_i32 s27, s27, 8
	v_lshlrev_b32_e32 v3, 5, v4
	v_and_b32_e32 v4, 0xc0, v7
	s_abs_i32 s35, s27
	v_sub_u32_e32 v4, v5, v4
	v_cvt_f32_u32_e32 v10, s35
	v_ashrrev_i16_sdwa v4, v239, sext(v4) dst_sel:DWORD dst_unused:UNUSED_PAD src0_sel:DWORD src1_sel:BYTE_0
	v_and_b32_e32 v3, 32, v3
	v_bfe_i32 v4, v4, 0, 16
	v_add_u32_e32 v7, v3, v4
	v_mul_lo_u32 v5, v8, s34
	v_add_lshl_u32 v176, v9, v7, 1
	v_add_lshl_u32 v132, v7, v5, 1
	v_rcp_iflag_f32_e32 v7, v10
	s_sub_i32 s36, 0, s35
	s_mulk_i32 s5, 0x160
	s_sub_i32 s4, s4, s5
	v_mul_f32_e32 v7, 0x4f7ffffe, v7
	v_cvt_u32_f32_e32 v7, v7
	s_abs_i32 s34, s4
	s_xor_b32 s5, s4, s27
	s_ashr_i32 s5, s5, 31
	v_readfirstlane_b32 s37, v7
	s_mul_i32 s36, s36, s37
	s_mul_hi_u32 s36, s37, s36
	s_add_i32 s37, s37, s36
	s_mul_hi_u32 s36, s34, s37
	s_mul_i32 s37, s36, s35
	s_sub_i32 s34, s34, s37
	s_add_i32 s37, s36, 1
	s_sub_i32 s38, s34, s35
	s_cmp_ge_u32 s34, s35
	s_cselect_b32 s36, s37, s36
	s_cselect_b32 s34, s38, s34
	s_add_i32 s37, s36, 1
	s_cmp_ge_u32 s34, s35
	s_cselect_b32 s34, s37, s36
	s_xor_b32 s34, s34, s5
	s_sub_i32 s38, s34, s5
	s_mul_i32 s5, s38, s27
	s_sub_i32 s4, s4, s5
	s_add_i32 s34, s17, s4
	s_and_b32 s100, s38, 1
	s_mul_i32 s100, s100, 22
	s_lshr_b32 s38, s38, 1
	s_add_i32 s38, s38, s100
	s_ashr_i32 s35, s34, 31
	s_ashr_i32 s39, s38, 31
	s_lshl_b64 s[36:37], s[34:35], 20
	s_lshl_b64 s[4:5], s[38:39], 20
	s_add_u32 s50, s15, s4
	s_addc_u32 s51, s26, s5
	s_add_i32 m0, s16, 0x10000
	v_readlane_b32 s40, v253, 52
	global_load_lds_dwordx4 v176, s[50:51]
	s_add_i32 m0, s16, 0x12000
	s_add_u32 s4, s50, s30
	global_load_lds_dwordx4 v128, s[50:51]
	s_addc_u32 s5, s51, s31
	s_add_i32 m0, s16, 0x14000
	v_readlane_b32 s41, v253, 53
	global_load_lds_dwordx4 v176, s[4:5]
	s_add_i32 m0, s16, 0x16000
	s_add_u32 s40, s40, s36
	s_addc_u32 s41, s41, s37
	s_add_i32 s35, s16, 0x2000
	global_load_lds_dwordx4 v128, s[4:5]
	s_mov_b32 m0, s16
	s_add_u32 s36, s40, s10
	global_load_lds_dwordx4 v132, s[40:41]
	s_mov_b32 m0, s35
	s_addc_u32 s37, s41, s11
	s_add_i32 s39, s16, 0x4000
	global_load_lds_dwordx4 v130, s[40:41]
	s_mov_b32 m0, s39
	s_add_i32 s72, s16, 0x6000
	global_load_lds_dwordx4 v132, s[36:37]
	s_mov_b32 m0, s72
	s_mov_b32 s1, s92
	global_load_lds_dwordx4 v130, s[36:37]
	v_readlane_b32 s36, v252, 58
	v_readlane_b32 s37, v252, 59
	s_andn2_b64 vcc, exec, s[36:37]
	s_cbranch_vccnz .LBB0_1116
	s_barrier

; template <int NN> __device__ __forceinline__ bool tile2d(int i, int nM, Unit& u) {
;     const long L = (long)i * (int)gridDim.x + (int)blockIdx.x; if (L >= nM * NN) return false;
;     tile_of_id<NN>((int)L, nM, u.pm, u.pn); u.kq = -1; return true;
.LBB0_1117:
	s_add_i32 s75, s75, 1
	s_mul_i32 s4, s91, s75
	s_mul_hi_u32 s5, s90, s75
	s_add_i32 s5, s5, s4
	s_mul_i32 s4, s90, s75
	s_add_u32 s4, s4, s2
	v_readlane_b32 s17, v252, 52
	s_addc_u32 s5, s5, s17
	v_mov_b64_e32 v[0:1], s[0:1]
	v_cmp_ge_i64_e64 s[36:37], s[4:5], v[0:1]
	s_and_b64 vcc, exec, s[36:37]
	s_cbranch_vccnz .LBB0_1119
	s_ashr_i32 s17, s4, 31
	s_lshr_b32 s17, s17, 29
	s_add_i32 s17, s4, s17
	s_ashr_i32 s27, s17, 3
	s_and_b32 s17, s17, -8
	s_sub_i32 s17, s4, s17
	s_cmp_lt_i32 s17, 0
	s_cselect_b32 s42, s14, s7
	s_mul_i32 s17, s42, s17
	s_add_i32 s17, s17, s27
	s_mul_hi_i32 s27, s17, 0x2e8ba2e9
	s_lshr_b32 s42, s27, 31
	s_ashr_i32 s27, s27, 6
	s_add_i32 s27, s27, s42
	s_lshl_b32 s43, s27, 3
	s_sub_i32 s42, s6, s43
	s_min_i32 s44, s42, 8
	s_abs_i32 s42, s44
	v_cvt_f32_u32_e32 v0, s42
	s_sub_i32 s46, 0, s42
	s_mulk_i32 s27, 0x160
	s_sub_i32 s17, s17, s27
	v_rcp_iflag_f32_e32 v0, v0
	s_abs_i32 s27, s17
	s_xor_b32 s45, s17, s44
	s_ashr_i32 s45, s45, 31
	v_mul_f32_e32 v0, 0x4f7ffffe, v0
	v_cvt_u32_f32_e32 v0, v0
	s_nop 0
	v_readfirstlane_b32 s47, v0
	s_mul_i32 s46, s46, s47
	s_mul_hi_u32 s46, s47, s46
	s_add_i32 s47, s47, s46
	s_mul_hi_u32 s46, s27, s47
	s_mul_i32 s47, s46, s42
	s_sub_i32 s27, s27, s47
	s_add_i32 s48, s46, 1
	s_sub_i32 s47, s27, s42
	s_cmp_ge_u32 s27, s42
	s_cselect_b32 s46, s48, s46
	s_cselect_b32 s27, s47, s27
	s_add_i32 s47, s46, 1
	s_cmp_ge_u32 s27, s42
	s_cselect_b32 s27, s47, s46
	s_xor_b32 s27, s27, s45
	s_sub_i32 s42, s27, s45
	s_mul_i32 s27, s42, s44
	s_sub_i32 s17, s17, s27
	s_add_i32 s44, s17, s43
	s_and_b32 s100, s42, 1
	s_mul_i32 s100, s100, 22
	s_lshr_b32 s42, s42, 1
	s_add_i32 s42, s42, s100
